# v033: v032 + kind-8 (residual) GEMM epilogue: per-group vmcnt(0) store drains removed (bf16 mode waits once per half for the staged loads; f32 mode waits right after its own loads)
# speedup vs baseline: 1.0070x; 1.0007x over previous
.LBB0_1166:
	v_lshlrev_b64 v[160:161], 10, v[180:181]
	v_lshl_add_u64 v[176:177], v[174:175], 0, s[4:5]
	v_lshl_add_u64 v[168:169], v[176:177], 0, v[160:161]
	v_cndmask_b32_e64 v160, 0, 1, s[20:21]
	v_cmp_ne_u32_e64 s[0:1], 1, v160
	s_andn2_b64 vcc, exec, s[20:21]
	v_lshl_add_u64 v[184:185], v[168:169], 2, s[64:65]
	s_cbranch_vccnz .LBB0_1242
	global_load_dwordx4 v[160:163], v[184:185], off
	global_load_dwordx4 v[164:167], v[184:185], off offset:16
	s_waitcnt vmcnt(0)
	s_cbranch_execnz .LBB0_1169

.LBB0_1169:
	s_waitcnt lgkmcnt(0)
	v_pk_add_f32 v[162:163], v[126:127], v[162:163]
	v_pk_add_f32 v[160:161], v[124:125], v[160:161]
	v_pk_add_f32 v[166:167], v[122:123], v[166:167]
	v_pk_add_f32 v[164:165], v[120:121], v[164:165]
	v_lshl_add_u64 v[182:183], v[168:169], 1, s[24:25]
	v_cvt_pk_bf16_f32 v168, v160, v161
	v_cvt_pk_bf16_f32 v169, v162, v163
	v_cvt_pk_bf16_f32 v170, v164, v165
	v_cvt_pk_bf16_f32 v171, v166, v167
	s_and_b64 vcc, exec, s[0:1]
	global_store_dwordx4 v[182:183], v[168:171], off
	s_cbranch_vccnz .LBB0_1243
	global_load_dwordx4 v[160:163], v[184:185], off offset:512
	global_load_dwordx4 v[164:167], v[184:185], off offset:528
	s_waitcnt vmcnt(0)
	s_cbranch_execnz .LBB0_1172
.LBB0_1171:
	s_waitcnt lgkmcnt(0)
	v_lshlrev_b32_e32 v160, 16, v152
	v_and_b32_e32 v161, 0xffff0000, v152
	v_lshlrev_b32_e32 v162, 16, v153
	v_and_b32_e32 v163, 0xffff0000, v153
	v_lshlrev_b32_e32 v164, 16, v154
	v_and_b32_e32 v165, 0xffff0000, v154
	v_lshlrev_b32_e32 v166, 16, v155
	v_and_b32_e32 v167, 0xffff0000, v155

.LBB0_1174:
	s_or_b64 exec, exec, s[20:21]
	s_or_b32 s5, s63, 16
	v_add_u32_e32 v180, s5, v172
	v_ashrrev_i32_e32 v181, 31, v180
	s_waitcnt lgkmcnt(0)
	v_lshlrev_b64 v[160:161], 10, v[180:181]
	v_lshl_add_u64 v[168:169], v[160:161], 0, v[176:177]
	s_and_b64 vcc, exec, s[0:1]
	v_lshl_add_u64 v[184:185], v[168:169], 2, s[64:65]
	s_cbranch_vccnz .LBB0_1244
	global_load_dwordx4 v[160:163], v[184:185], off
	global_load_dwordx4 v[164:167], v[184:185], off offset:16
	s_waitcnt vmcnt(0)
	s_cbranch_execnz .LBB0_1177
.LBB0_1176:
	s_waitcnt lgkmcnt(0)
	v_lshlrev_b32_e32 v160, 16, v148
	v_and_b32_e32 v161, 0xffff0000, v148
	v_lshlrev_b32_e32 v162, 16, v149
	v_and_b32_e32 v163, 0xffff0000, v149
	v_lshlrev_b32_e32 v164, 16, v150
	v_and_b32_e32 v165, 0xffff0000, v150
	v_lshlrev_b32_e32 v166, 16, v151
	v_and_b32_e32 v167, 0xffff0000, v151
.LBB0_1177:
	s_waitcnt lgkmcnt(0)
	v_pk_add_f32 v[162:163], v[118:119], v[162:163]
	v_pk_add_f32 v[160:161], v[116:117], v[160:161]
	v_pk_add_f32 v[166:167], v[114:115], v[166:167]
	v_pk_add_f32 v[164:165], v[112:113], v[164:165]
	v_lshl_add_u64 v[182:183], v[168:169], 1, s[24:25]
	v_cvt_pk_bf16_f32 v168, v160, v161
	v_cvt_pk_bf16_f32 v169, v162, v163
	v_cvt_pk_bf16_f32 v170, v164, v165
	v_cvt_pk_bf16_f32 v171, v166, v167
	s_and_b64 vcc, exec, s[0:1]
	global_store_dwordx4 v[182:183], v[168:171], off
	s_cbranch_vccnz .LBB0_1245
	global_load_dwordx4 v[160:163], v[184:185], off offset:512
	global_load_dwordx4 v[164:167], v[184:185], off offset:528
	s_waitcnt vmcnt(0)
	s_cbranch_execnz .LBB0_1180
.LBB0_1179:
	s_waitcnt lgkmcnt(0)
	v_lshlrev_b32_e32 v160, 16, v144
	v_and_b32_e32 v161, 0xffff0000, v144
	v_lshlrev_b32_e32 v162, 16, v145
	v_and_b32_e32 v163, 0xffff0000, v145
	v_lshlrev_b32_e32 v164, 16, v146
	v_and_b32_e32 v165, 0xffff0000, v146
	v_lshlrev_b32_e32 v166, 16, v147
	v_and_b32_e32 v167, 0xffff0000, v147

.LBB0_1184:
	s_or_b32 s16, s63, 32
	v_add_u32_e32 v180, s16, v172
	v_ashrrev_i32_e32 v181, 31, v180
	s_waitcnt lgkmcnt(0)
	v_lshlrev_b64 v[160:161], 10, v[180:181]
	v_lshl_add_u64 v[168:169], v[160:161], 0, v[176:177]
	s_and_b64 vcc, exec, s[0:1]
	v_lshl_add_u64 v[184:185], v[168:169], 2, s[64:65]
	s_cbranch_vccnz .LBB0_1246
	global_load_dwordx4 v[160:163], v[184:185], off
	global_load_dwordx4 v[164:167], v[184:185], off offset:16
	s_waitcnt vmcnt(0)
	s_cbranch_execnz .LBB0_1187
.LBB0_1186:
	s_waitcnt lgkmcnt(0)
	v_lshlrev_b32_e32 v160, 16, v140
	v_and_b32_e32 v161, 0xffff0000, v140
	v_lshlrev_b32_e32 v162, 16, v141
	v_and_b32_e32 v163, 0xffff0000, v141
	v_lshlrev_b32_e32 v164, 16, v142
	v_and_b32_e32 v165, 0xffff0000, v142
	v_lshlrev_b32_e32 v166, 16, v143
	v_and_b32_e32 v167, 0xffff0000, v143
.LBB0_1187:
	s_waitcnt lgkmcnt(0)
	v_pk_add_f32 v[162:163], v[110:111], v[162:163]
	v_pk_add_f32 v[160:161], v[108:109], v[160:161]
	v_pk_add_f32 v[166:167], v[106:107], v[166:167]
	v_pk_add_f32 v[164:165], v[104:105], v[164:165]
	v_lshl_add_u64 v[182:183], v[168:169], 1, s[24:25]
	v_cvt_pk_bf16_f32 v168, v160, v161
	v_cvt_pk_bf16_f32 v169, v162, v163
	v_cvt_pk_bf16_f32 v170, v164, v165
	v_cvt_pk_bf16_f32 v171, v166, v167
	s_and_b64 vcc, exec, s[0:1]
	global_store_dwordx4 v[182:183], v[168:171], off
	s_cbranch_vccnz .LBB0_1247
	global_load_dwordx4 v[160:163], v[184:185], off offset:512
	global_load_dwordx4 v[164:167], v[184:185], off offset:528
	s_waitcnt vmcnt(0)
	s_cbranch_execnz .LBB0_1190
.LBB0_1189:
	s_waitcnt lgkmcnt(0)
	v_lshlrev_b32_e32 v160, 16, v136
	v_and_b32_e32 v161, 0xffff0000, v136
	v_lshlrev_b32_e32 v162, 16, v137
	v_and_b32_e32 v163, 0xffff0000, v137
	v_lshlrev_b32_e32 v164, 16, v138
	v_and_b32_e32 v165, 0xffff0000, v138
	v_lshlrev_b32_e32 v166, 16, v139
	v_and_b32_e32 v167, 0xffff0000, v139

.LBB0_1192:
	s_or_b64 exec, exec, s[20:21]
	s_or_b32 s17, s63, 48
	v_add_u32_e32 v180, s17, v172
	v_ashrrev_i32_e32 v181, 31, v180
	s_waitcnt lgkmcnt(0)
	v_lshlrev_b64 v[160:161], 10, v[180:181]
	v_lshl_add_u64 v[168:169], v[160:161], 0, v[176:177]
	s_and_b64 vcc, exec, s[0:1]
	v_lshl_add_u64 v[184:185], v[168:169], 2, s[64:65]
	s_cbranch_vccnz .LBB0_1248
	global_load_dwordx4 v[160:163], v[184:185], off
	global_load_dwordx4 v[164:167], v[184:185], off offset:16
	s_waitcnt vmcnt(0)
	s_cbranch_execnz .LBB0_1195
.LBB0_1194:
	s_waitcnt lgkmcnt(0)
	v_lshlrev_b32_e32 v160, 16, v132
	v_and_b32_e32 v161, 0xffff0000, v132
	v_lshlrev_b32_e32 v162, 16, v133
	v_and_b32_e32 v163, 0xffff0000, v133
	v_lshlrev_b32_e32 v164, 16, v134
	v_and_b32_e32 v165, 0xffff0000, v134
	v_lshlrev_b32_e32 v166, 16, v135
	v_and_b32_e32 v167, 0xffff0000, v135
.LBB0_1195:
	s_waitcnt lgkmcnt(0)
	v_pk_add_f32 v[162:163], v[102:103], v[162:163]
	v_pk_add_f32 v[160:161], v[100:101], v[160:161]
	v_pk_add_f32 v[166:167], v[98:99], v[166:167]
	v_pk_add_f32 v[164:165], v[96:97], v[164:165]
	v_lshl_add_u64 v[182:183], v[168:169], 1, s[24:25]
	v_cvt_pk_bf16_f32 v168, v160, v161
	v_cvt_pk_bf16_f32 v169, v162, v163
	v_cvt_pk_bf16_f32 v170, v164, v165
	v_cvt_pk_bf16_f32 v171, v166, v167
	s_and_b64 vcc, exec, s[0:1]
	global_store_dwordx4 v[182:183], v[168:171], off
	s_cbranch_vccnz .LBB0_1249
	global_load_dwordx4 v[160:163], v[184:185], off offset:512
	global_load_dwordx4 v[164:167], v[184:185], off offset:528
	s_waitcnt vmcnt(0)
	s_cbranch_execnz .LBB0_1198
.LBB0_1197:
	s_waitcnt lgkmcnt(0)
	v_lshlrev_b32_e32 v160, 16, v128
	v_and_b32_e32 v161, 0xffff0000, v128
	v_lshlrev_b32_e32 v162, 16, v129
	v_and_b32_e32 v163, 0xffff0000, v129
	v_lshlrev_b32_e32 v164, 16, v130
	v_and_b32_e32 v165, 0xffff0000, v130
	v_lshlrev_b32_e32 v166, 16, v131
	v_and_b32_e32 v167, 0xffff0000, v131

.LBB0_1205:
	s_waitcnt lgkmcnt(0)
	v_lshlrev_b64 v[160:161], 10, v[168:169]
	v_lshl_add_u64 v[170:171], v[160:161], 0, v[176:177]
	s_and_b64 vcc, exec, s[0:1]
	v_lshl_add_u64 v[178:179], v[170:171], 2, s[64:65]
	s_cbranch_vccnz .LBB0_1251
	global_load_dwordx4 v[160:163], v[178:179], off
	global_load_dwordx4 v[164:167], v[178:179], off offset:16
	s_waitcnt vmcnt(0)
	s_cbranch_execnz .LBB0_1208

.LBB0_1208:
	s_waitcnt lgkmcnt(0)
	v_pk_add_f32 v[156:157], v[62:63], v[162:163]
	v_pk_add_f32 v[158:159], v[60:61], v[160:161]
	v_pk_add_f32 v[160:161], v[58:59], v[166:167]
	v_pk_add_f32 v[162:163], v[56:57], v[164:165]
	v_lshl_add_u64 v[170:171], v[170:171], 1, s[24:25]
	v_cvt_pk_bf16_f32 v164, v158, v159
	v_cvt_pk_bf16_f32 v165, v156, v157
	v_cvt_pk_bf16_f32 v166, v162, v163
	v_cvt_pk_bf16_f32 v167, v160, v161
	s_and_b64 vcc, exec, s[0:1]
	global_store_dwordx4 v[170:171], v[164:167], off
	s_cbranch_vccnz .LBB0_1252
	global_load_dwordx4 v[156:159], v[178:179], off offset:512
	global_load_dwordx4 v[160:163], v[178:179], off offset:528
	s_waitcnt vmcnt(0)
	s_cbranch_execnz .LBB0_1211
.LBB0_1210:
	s_waitcnt lgkmcnt(0)
	v_lshlrev_b32_e32 v156, 16, v152
	v_and_b32_e32 v157, 0xffff0000, v152
	v_lshlrev_b32_e32 v158, 16, v153
	v_and_b32_e32 v159, 0xffff0000, v153
	v_lshlrev_b32_e32 v160, 16, v154
	v_and_b32_e32 v161, 0xffff0000, v154
	v_lshlrev_b32_e32 v162, 16, v155
	v_and_b32_e32 v163, 0xffff0000, v155
.LBB0_1211:
	v_and_b32_e32 v153, 0xffff0000, v164
	v_lshlrev_b32_e32 v152, 16, v164
	v_and_b32_e32 v155, 0xffff0000, v165
	v_mul_f32_e32 v153, v153, v153
	v_lshlrev_b32_e32 v154, 16, v165
	v_fmac_f32_e32 v153, v152, v152
	v_mul_f32_e32 v152, v155, v155
	v_and_b32_e32 v165, 0xffff0000, v166
	v_fmac_f32_e32 v152, v154, v154
	v_lshlrev_b32_e32 v164, 16, v166
	v_add_f32_e32 v152, v153, v152
	v_mul_f32_e32 v153, v165, v165
	v_lshlrev_b32_e32 v166, 16, v167
	v_and_b32_e32 v167, 0xffff0000, v167
	v_fmac_f32_e32 v153, v164, v164
	v_add_f32_e32 v152, v153, v152
	v_mul_f32_e32 v153, v167, v167
	v_fmac_f32_e32 v153, v166, v166
	s_waitcnt lgkmcnt(0)
	v_pk_add_f32 v[154:155], v[28:29], v[156:157]
	v_add_f32_e32 v164, v153, v152
	v_pk_add_f32 v[152:153], v[30:31], v[158:159]
	v_cvt_pk_bf16_f32 v154, v154, v155
	v_pk_add_f32 v[158:159], v[26:27], v[162:163]
	v_pk_add_f32 v[156:157], v[24:25], v[160:161]
	v_cvt_pk_bf16_f32 v155, v152, v153
	v_and_b32_e32 v153, 0xffff0000, v154
	v_cvt_pk_bf16_f32 v156, v156, v157
	v_cvt_pk_bf16_f32 v157, v158, v159
	v_lshlrev_b32_e32 v152, 16, v154
	v_and_b32_e32 v159, 0xffff0000, v155
	v_mul_f32_e32 v153, v153, v153
	v_lshlrev_b32_e32 v158, 16, v155
	v_fmac_f32_e32 v153, v152, v152
	v_mul_f32_e32 v152, v159, v159
	v_and_b32_e32 v161, 0xffff0000, v156
	v_fmac_f32_e32 v152, v158, v158
	v_lshlrev_b32_e32 v160, 16, v156
	v_add_f32_e32 v152, v153, v152
	v_mul_f32_e32 v153, v161, v161
	v_and_b32_e32 v163, 0xffff0000, v157
	v_fmac_f32_e32 v153, v160, v160
	v_lshlrev_b32_e32 v162, 16, v157
	v_add_f32_e32 v152, v153, v152
	v_mul_f32_e32 v153, v163, v163
	v_fmac_f32_e32 v153, v162, v162
	v_add_f32_e32 v152, v153, v152
	v_add_f32_e32 v152, v164, v152
	ds_bpermute_b32 v153, v173, v152
	global_store_dwordx4 v[170:171], v[154:157], off offset:256
	s_waitcnt lgkmcnt(0)
	v_add_f32_e32 v152, v152, v153
	ds_bpermute_b32 v153, v175, v152
	s_and_saveexec_b64 s[20:21], s[40:41]
	s_cbranch_execz .LBB0_1213
	s_waitcnt lgkmcnt(0)
	v_add_f32_e32 v154, v152, v153
	s_lshl_b32 s54, s75, 2
	v_lshlrev_b64 v[152:153], 6, v[168:169]
	s_ashr_i32 s55, s54, 31
	v_lshl_add_u64 v[152:153], s[26:27], 0, v[152:153]
	v_lshl_add_u64 v[152:153], s[54:55], 2, v[152:153]
	s_lshl_b32 s82, s56, 2
	v_lshl_add_u64 v[152:153], v[152:153], 0, s[82:83]
	global_store_dword v[152:153], v154, off
.LBB0_1213:
	s_or_b64 exec, exec, s[20:21]
	v_add_u32_e32 v160, s5, v180
	v_ashrrev_i32_e32 v161, 31, v160
	s_waitcnt lgkmcnt(0)
	v_lshlrev_b64 v[152:153], 10, v[160:161]
	v_lshl_add_u64 v[162:163], v[152:153], 0, v[176:177]
	s_and_b64 vcc, exec, s[0:1]
	v_lshl_add_u64 v[164:165], v[162:163], 2, s[64:65]
	s_cbranch_vccnz .LBB0_1253
	global_load_dwordx4 v[152:155], v[164:165], off
	global_load_dwordx4 v[156:159], v[164:165], off offset:16
	s_waitcnt vmcnt(0)
	s_cbranch_execnz .LBB0_1216
.LBB0_1215:
	s_waitcnt lgkmcnt(0)
	v_lshlrev_b32_e32 v152, 16, v148
	v_and_b32_e32 v153, 0xffff0000, v148
	v_lshlrev_b32_e32 v154, 16, v149
	v_and_b32_e32 v155, 0xffff0000, v149
	v_lshlrev_b32_e32 v156, 16, v150
	v_and_b32_e32 v157, 0xffff0000, v150
	v_lshlrev_b32_e32 v158, 16, v151
	v_and_b32_e32 v159, 0xffff0000, v151
.LBB0_1216:
	s_waitcnt lgkmcnt(0)
	v_pk_add_f32 v[148:149], v[54:55], v[154:155]
	v_pk_add_f32 v[150:151], v[52:53], v[152:153]
	v_pk_add_f32 v[152:153], v[50:51], v[158:159]
	v_pk_add_f32 v[154:155], v[48:49], v[156:157]
	v_lshl_add_u64 v[162:163], v[162:163], 1, s[24:25]
	v_cvt_pk_bf16_f32 v156, v150, v151
	v_cvt_pk_bf16_f32 v157, v148, v149
	v_cvt_pk_bf16_f32 v158, v154, v155
	v_cvt_pk_bf16_f32 v159, v152, v153
	s_and_b64 vcc, exec, s[0:1]
	global_store_dwordx4 v[162:163], v[156:159], off
	s_cbranch_vccnz .LBB0_1254
	global_load_dwordx4 v[148:151], v[164:165], off offset:512
	global_load_dwordx4 v[152:155], v[164:165], off offset:528
	s_waitcnt vmcnt(0)
	s_cbranch_execnz .LBB0_1219
.LBB0_1218:
	s_waitcnt lgkmcnt(0)
	v_lshlrev_b32_e32 v148, 16, v144
	v_and_b32_e32 v149, 0xffff0000, v144
	v_lshlrev_b32_e32 v150, 16, v145
	v_and_b32_e32 v151, 0xffff0000, v145
	v_lshlrev_b32_e32 v152, 16, v146
	v_and_b32_e32 v153, 0xffff0000, v146
	v_lshlrev_b32_e32 v154, 16, v147
	v_and_b32_e32 v155, 0xffff0000, v147
.LBB0_1219:
	v_and_b32_e32 v145, 0xffff0000, v156
	v_lshlrev_b32_e32 v144, 16, v156
	v_and_b32_e32 v147, 0xffff0000, v157
	v_mul_f32_e32 v145, v145, v145
	v_lshlrev_b32_e32 v146, 16, v157
	v_fmac_f32_e32 v145, v144, v144
	v_mul_f32_e32 v144, v147, v147
	v_and_b32_e32 v157, 0xffff0000, v158
	v_fmac_f32_e32 v144, v146, v146
	v_lshlrev_b32_e32 v156, 16, v158
	v_add_f32_e32 v144, v145, v144
	v_mul_f32_e32 v145, v157, v157
	v_lshlrev_b32_e32 v158, 16, v159
	v_and_b32_e32 v159, 0xffff0000, v159
	v_fmac_f32_e32 v145, v156, v156
	v_add_f32_e32 v144, v145, v144
	v_mul_f32_e32 v145, v159, v159
	v_fmac_f32_e32 v145, v158, v158
	s_waitcnt lgkmcnt(0)
	v_pk_add_f32 v[146:147], v[20:21], v[148:149]
	v_add_f32_e32 v156, v145, v144
	v_pk_add_f32 v[144:145], v[22:23], v[150:151]
	v_cvt_pk_bf16_f32 v146, v146, v147
	v_pk_add_f32 v[150:151], v[18:19], v[154:155]
	v_pk_add_f32 v[148:149], v[16:17], v[152:153]
	v_cvt_pk_bf16_f32 v147, v144, v145
	v_and_b32_e32 v145, 0xffff0000, v146
	v_cvt_pk_bf16_f32 v148, v148, v149
	v_cvt_pk_bf16_f32 v149, v150, v151
	v_lshlrev_b32_e32 v144, 16, v146
	v_and_b32_e32 v151, 0xffff0000, v147
	v_mul_f32_e32 v145, v145, v145
	v_lshlrev_b32_e32 v150, 16, v147
	v_fmac_f32_e32 v145, v144, v144
	v_mul_f32_e32 v144, v151, v151
	v_and_b32_e32 v153, 0xffff0000, v148
	v_fmac_f32_e32 v144, v150, v150
	v_lshlrev_b32_e32 v152, 16, v148
	v_add_f32_e32 v144, v145, v144
	v_mul_f32_e32 v145, v153, v153
	v_and_b32_e32 v155, 0xffff0000, v149
	v_fmac_f32_e32 v145, v152, v152
	v_lshlrev_b32_e32 v154, 16, v149
	v_add_f32_e32 v144, v145, v144
	v_mul_f32_e32 v145, v155, v155
	v_fmac_f32_e32 v145, v154, v154
	v_add_f32_e32 v144, v145, v144
	v_add_f32_e32 v144, v156, v144
	ds_bpermute_b32 v145, v173, v144
	global_store_dwordx4 v[162:163], v[146:149], off offset:256
	s_waitcnt lgkmcnt(0)
	v_add_f32_e32 v144, v144, v145
	ds_bpermute_b32 v145, v175, v144
	s_and_saveexec_b64 s[20:21], s[40:41]
	s_cbranch_execz .LBB0_1221
	s_waitcnt lgkmcnt(0)
	v_add_f32_e32 v146, v144, v145
	s_lshl_b32 s54, s75, 2
	v_lshlrev_b64 v[144:145], 6, v[160:161]
	s_ashr_i32 s55, s54, 31
	v_lshl_add_u64 v[144:145], s[26:27], 0, v[144:145]
	v_lshl_add_u64 v[144:145], s[54:55], 2, v[144:145]
	s_lshl_b32 s82, s56, 2
	v_lshl_add_u64 v[144:145], v[144:145], 0, s[82:83]
	global_store_dword v[144:145], v146, off

.LBB0_1223:
	v_add_u32_e32 v152, s16, v180
	v_ashrrev_i32_e32 v153, 31, v152
	s_waitcnt lgkmcnt(0)
	v_lshlrev_b64 v[144:145], 10, v[152:153]
	v_lshl_add_u64 v[154:155], v[144:145], 0, v[176:177]
	s_and_b64 vcc, exec, s[0:1]
	v_lshl_add_u64 v[156:157], v[154:155], 2, s[64:65]
	s_cbranch_vccnz .LBB0_1255
	global_load_dwordx4 v[144:147], v[156:157], off
	global_load_dwordx4 v[148:151], v[156:157], off offset:16
	s_waitcnt vmcnt(0)
	s_cbranch_execnz .LBB0_1226
.LBB0_1225:
	s_waitcnt lgkmcnt(0)
	v_lshlrev_b32_e32 v144, 16, v140
	v_and_b32_e32 v145, 0xffff0000, v140
	v_lshlrev_b32_e32 v146, 16, v141
	v_and_b32_e32 v147, 0xffff0000, v141
	v_lshlrev_b32_e32 v148, 16, v142
	v_and_b32_e32 v149, 0xffff0000, v142
	v_lshlrev_b32_e32 v150, 16, v143
	v_and_b32_e32 v151, 0xffff0000, v143
.LBB0_1226:
	s_waitcnt lgkmcnt(0)
	v_pk_add_f32 v[140:141], v[46:47], v[146:147]
	v_pk_add_f32 v[142:143], v[44:45], v[144:145]
	v_pk_add_f32 v[144:145], v[42:43], v[150:151]
	v_pk_add_f32 v[146:147], v[40:41], v[148:149]
	v_lshl_add_u64 v[154:155], v[154:155], 1, s[24:25]
	v_cvt_pk_bf16_f32 v148, v142, v143
	v_cvt_pk_bf16_f32 v149, v140, v141
	v_cvt_pk_bf16_f32 v150, v146, v147
	v_cvt_pk_bf16_f32 v151, v144, v145
	s_and_b64 vcc, exec, s[0:1]
	global_store_dwordx4 v[154:155], v[148:151], off
	s_cbranch_vccnz .LBB0_1256
	global_load_dwordx4 v[140:143], v[156:157], off offset:512
	global_load_dwordx4 v[144:147], v[156:157], off offset:528
	s_waitcnt vmcnt(0)
	s_cbranch_execnz .LBB0_1229
.LBB0_1228:
	s_waitcnt lgkmcnt(0)
	v_lshlrev_b32_e32 v140, 16, v136
	v_and_b32_e32 v141, 0xffff0000, v136
	v_lshlrev_b32_e32 v142, 16, v137
	v_and_b32_e32 v143, 0xffff0000, v137
	v_lshlrev_b32_e32 v144, 16, v138
	v_and_b32_e32 v145, 0xffff0000, v138
	v_lshlrev_b32_e32 v146, 16, v139
	v_and_b32_e32 v147, 0xffff0000, v139
.LBB0_1229:
	v_and_b32_e32 v137, 0xffff0000, v148
	v_lshlrev_b32_e32 v136, 16, v148
	v_and_b32_e32 v139, 0xffff0000, v149
	v_mul_f32_e32 v137, v137, v137
	v_lshlrev_b32_e32 v138, 16, v149
	v_fmac_f32_e32 v137, v136, v136
	v_mul_f32_e32 v136, v139, v139
	v_and_b32_e32 v149, 0xffff0000, v150
	v_fmac_f32_e32 v136, v138, v138
	v_lshlrev_b32_e32 v148, 16, v150
	v_add_f32_e32 v136, v137, v136
	v_mul_f32_e32 v137, v149, v149
	v_lshlrev_b32_e32 v150, 16, v151
	v_and_b32_e32 v151, 0xffff0000, v151
	v_fmac_f32_e32 v137, v148, v148
	v_add_f32_e32 v136, v137, v136
	v_mul_f32_e32 v137, v151, v151
	v_fmac_f32_e32 v137, v150, v150
	s_waitcnt lgkmcnt(0)
	v_pk_add_f32 v[138:139], v[12:13], v[140:141]
	v_add_f32_e32 v148, v137, v136
	v_pk_add_f32 v[136:137], v[14:15], v[142:143]
	v_cvt_pk_bf16_f32 v138, v138, v139
	v_pk_add_f32 v[142:143], v[10:11], v[146:147]
	v_pk_add_f32 v[140:141], v[8:9], v[144:145]
	v_cvt_pk_bf16_f32 v139, v136, v137
	v_and_b32_e32 v137, 0xffff0000, v138
	v_cvt_pk_bf16_f32 v140, v140, v141
	v_cvt_pk_bf16_f32 v141, v142, v143
	v_lshlrev_b32_e32 v136, 16, v138
	v_and_b32_e32 v143, 0xffff0000, v139
	v_mul_f32_e32 v137, v137, v137
	v_lshlrev_b32_e32 v142, 16, v139
	v_fmac_f32_e32 v137, v136, v136
	v_mul_f32_e32 v136, v143, v143
	v_and_b32_e32 v145, 0xffff0000, v140
	v_fmac_f32_e32 v136, v142, v142
	v_lshlrev_b32_e32 v144, 16, v140
	v_add_f32_e32 v136, v137, v136
	v_mul_f32_e32 v137, v145, v145
	v_and_b32_e32 v147, 0xffff0000, v141
	v_fmac_f32_e32 v137, v144, v144
	v_lshlrev_b32_e32 v146, 16, v141
	v_add_f32_e32 v136, v137, v136
	v_mul_f32_e32 v137, v147, v147
	v_fmac_f32_e32 v137, v146, v146
	v_add_f32_e32 v136, v137, v136
	v_add_f32_e32 v136, v148, v136
	ds_bpermute_b32 v137, v173, v136
	global_store_dwordx4 v[154:155], v[138:141], off offset:256
	s_waitcnt lgkmcnt(0)
	v_add_f32_e32 v136, v136, v137
	ds_bpermute_b32 v137, v175, v136
	s_and_saveexec_b64 s[20:21], s[40:41]
	s_cbranch_execz .LBB0_1231
	s_waitcnt lgkmcnt(0)
	v_add_f32_e32 v138, v136, v137
	s_lshl_b32 s54, s75, 2
	v_lshlrev_b64 v[136:137], 6, v[152:153]
	s_ashr_i32 s55, s54, 31
	v_lshl_add_u64 v[136:137], s[26:27], 0, v[136:137]
	v_lshl_add_u64 v[136:137], s[54:55], 2, v[136:137]
	s_lshl_b32 s82, s56, 2
	v_lshl_add_u64 v[136:137], v[136:137], 0, s[82:83]
	global_store_dword v[136:137], v138, off
.LBB0_1231:
	s_or_b64 exec, exec, s[20:21]
	v_add_u32_e32 v144, s17, v180
	v_ashrrev_i32_e32 v145, 31, v144
	s_waitcnt lgkmcnt(0)
	v_lshlrev_b64 v[136:137], 10, v[144:145]
	v_lshl_add_u64 v[146:147], v[136:137], 0, v[176:177]
	s_and_b64 vcc, exec, s[0:1]
	v_lshl_add_u64 v[148:149], v[146:147], 2, s[64:65]
	s_cbranch_vccnz .LBB0_1257
	global_load_dwordx4 v[136:139], v[148:149], off
	global_load_dwordx4 v[140:143], v[148:149], off offset:16
	s_waitcnt vmcnt(0)
	s_cbranch_execnz .LBB0_1234
.LBB0_1233:
	s_waitcnt lgkmcnt(0)
	v_lshlrev_b32_e32 v136, 16, v132
	v_and_b32_e32 v137, 0xffff0000, v132
	v_lshlrev_b32_e32 v138, 16, v133
	v_and_b32_e32 v139, 0xffff0000, v133
	v_lshlrev_b32_e32 v140, 16, v134
	v_and_b32_e32 v141, 0xffff0000, v134
	v_lshlrev_b32_e32 v142, 16, v135
	v_and_b32_e32 v143, 0xffff0000, v135
.LBB0_1234:
	s_waitcnt lgkmcnt(0)
	v_pk_add_f32 v[132:133], v[38:39], v[138:139]
	v_pk_add_f32 v[134:135], v[36:37], v[136:137]
	v_pk_add_f32 v[136:137], v[34:35], v[142:143]
	v_pk_add_f32 v[138:139], v[32:33], v[140:141]
	v_lshl_add_u64 v[146:147], v[146:147], 1, s[24:25]
	v_cvt_pk_bf16_f32 v140, v134, v135
	v_cvt_pk_bf16_f32 v141, v132, v133
	v_cvt_pk_bf16_f32 v142, v138, v139
	v_cvt_pk_bf16_f32 v143, v136, v137
	s_and_b64 vcc, exec, s[0:1]
	global_store_dwordx4 v[146:147], v[140:143], off
	s_cbranch_vccnz .LBB0_1258
	global_load_dwordx4 v[132:135], v[148:149], off offset:512
	global_load_dwordx4 v[136:139], v[148:149], off offset:528
	s_waitcnt vmcnt(0)
	s_cbranch_execnz .LBB0_1237
.LBB0_1236:
	s_waitcnt lgkmcnt(0)
	v_lshlrev_b32_e32 v132, 16, v128
	v_and_b32_e32 v133, 0xffff0000, v128
	v_lshlrev_b32_e32 v134, 16, v129
	v_and_b32_e32 v135, 0xffff0000, v129
	v_lshlrev_b32_e32 v136, 16, v130
	v_and_b32_e32 v137, 0xffff0000, v130
	v_lshlrev_b32_e32 v138, 16, v131
	v_and_b32_e32 v139, 0xffff0000, v131
.LBB0_1237:
	v_and_b32_e32 v129, 0xffff0000, v140
	v_lshlrev_b32_e32 v128, 16, v140
	v_and_b32_e32 v131, 0xffff0000, v141
	v_mul_f32_e32 v129, v129, v129
	v_lshlrev_b32_e32 v130, 16, v141
	v_fmac_f32_e32 v129, v128, v128
	v_mul_f32_e32 v128, v131, v131
	v_and_b32_e32 v141, 0xffff0000, v142
	v_fmac_f32_e32 v128, v130, v130
	v_lshlrev_b32_e32 v140, 16, v142
	v_add_f32_e32 v128, v129, v128
	v_mul_f32_e32 v129, v141, v141
	v_lshlrev_b32_e32 v142, 16, v143
	v_and_b32_e32 v143, 0xffff0000, v143
	v_fmac_f32_e32 v129, v140, v140
	v_add_f32_e32 v128, v129, v128
	v_mul_f32_e32 v129, v143, v143
	v_fmac_f32_e32 v129, v142, v142
	s_waitcnt lgkmcnt(0)
	v_pk_add_f32 v[130:131], v[4:5], v[132:133]
	v_add_f32_e32 v140, v129, v128
	v_pk_add_f32 v[128:129], v[6:7], v[134:135]
	v_cvt_pk_bf16_f32 v130, v130, v131
	v_pk_add_f32 v[134:135], v[2:3], v[138:139]
	v_pk_add_f32 v[132:133], v[0:1], v[136:137]
	v_cvt_pk_bf16_f32 v131, v128, v129
	v_and_b32_e32 v129, 0xffff0000, v130
	v_cvt_pk_bf16_f32 v132, v132, v133
	v_cvt_pk_bf16_f32 v133, v134, v135
	v_lshlrev_b32_e32 v128, 16, v130
	v_and_b32_e32 v135, 0xffff0000, v131
	v_mul_f32_e32 v129, v129, v129
	v_lshlrev_b32_e32 v134, 16, v131
	v_fmac_f32_e32 v129, v128, v128
	v_mul_f32_e32 v128, v135, v135
	v_and_b32_e32 v137, 0xffff0000, v132
	v_fmac_f32_e32 v128, v134, v134
	v_lshlrev_b32_e32 v136, 16, v132
	v_add_f32_e32 v128, v129, v128
	v_mul_f32_e32 v129, v137, v137
	v_and_b32_e32 v139, 0xffff0000, v133
	v_fmac_f32_e32 v129, v136, v136
	v_lshlrev_b32_e32 v138, 16, v133
	v_add_f32_e32 v128, v129, v128
	v_mul_f32_e32 v129, v139, v139
	v_fmac_f32_e32 v129, v138, v138
	v_add_f32_e32 v128, v129, v128
	v_add_f32_e32 v128, v140, v128
	ds_bpermute_b32 v129, v173, v128
	global_store_dwordx4 v[146:147], v[130:133], off offset:256
	s_waitcnt lgkmcnt(0)
	v_add_f32_e32 v128, v128, v129
	ds_bpermute_b32 v129, v175, v128
	s_and_saveexec_b64 s[20:21], s[40:41]
	s_cbranch_execz .LBB0_1239
	s_waitcnt lgkmcnt(0)
	v_add_f32_e32 v130, v128, v129
	s_lshl_b32 s16, s75, 2
	v_lshlrev_b64 v[128:129], 6, v[144:145]
	s_ashr_i32 s17, s16, 31
	v_lshl_add_u64 v[128:129], s[26:27], 0, v[128:129]
	v_lshl_add_u64 v[128:129], s[16:17], 2, v[128:129]
	s_lshl_b32 s82, s56, 2
	v_lshl_add_u64 v[128:129], v[128:129], 0, s[82:83]
	global_store_dword v[128:129], v130, off
